# P2 heavy (q/k) epilogue: rope-table loads of row groups 1-6 issued with group 0's, group 7's at group 1; the per-group full vmcnt drain (previous group's stores) removed for groups 1-6
# speedup vs baseline: 1.0007x; 1.0007x over previous
.LBB0_241:
	s_or_b64 exec, exec, s[62:63]
	s_cmp_gt_i32 s53, 3
	s_mov_b32 s7, 0x11000000
	s_cselect_b32 s7, s7, 0x10000000
	s_cselect_b32 s0, s36, s30
	s_cselect_b32 s1, s37, s31
	s_add_u32 s7, s54, s7
	s_addc_u32 s51, s55, 0
	s_lshl_b32 s15, s53, 1
	s_and_b32 s14, s6, -8
	s_and_b32 s15, s15, 6
	s_or_b32 s62, s15, s14
	s_ashr_i32 s63, s62, 31
	s_lshl_b64 s[14:15], s[62:63], 19
	s_add_u32 s7, s7, s14
	s_addc_u32 s15, s51, s15
	s_lshl_b32 s14, s8, 16
	s_add_u32 s14, s7, s14
	s_addc_u32 s15, s15, 0
	s_ashr_i32 s7, s6, 31
	v_ashrrev_i32_e32 v163, 31, v162
	s_lshl_b64 s[64:65], s[6:7], 14
	v_add_u32_e32 v164, s82, v104
	v_lshlrev_b64 v[136:137], 6, v[162:163]
	v_ashrrev_i32_e32 v165, 31, v164
	v_lshl_add_u64 v[136:137], v[136:137], 0, s[64:65]
	v_lshlrev_b64 v[168:169], 2, v[164:165]
	v_lshlrev_b64 v[140:141], 2, v[136:137]
	s_waitcnt lgkmcnt(0)
	s_barrier
	v_lshl_add_u64 v[104:105], s[0:1], 0, v[168:169]
	v_lshl_add_u64 v[136:137], s[28:29], 0, v[140:141]
	v_lshl_add_u64 v[140:141], s[40:41], 0, v[140:141]
	global_load_dwordx4 v[108:111], v[104:105], off
	s_waitcnt lgkmcnt(0)
	global_load_dwordx4 v[104:107], v[104:105], off offset:256
	v_lshl_add_u64 v[136:137], v[136:137], 0, v[168:169]
	v_lshl_add_u64 v[140:141], v[140:141], 0, v[168:169]
	v_mov_b64_e32 v[246:247], v[136:137]
	v_mov_b64_e32 v[248:249], v[140:141]
	s_mov_b32 s98, 0x1000
	s_mov_b32 s99, 0
	v_lshl_add_u64 v[250:251], v[246:247], 0, s[98:99]
	global_load_dwordx4 v[178:181], v[250:251], off
	v_lshl_add_u64 v[250:251], v[248:249], 0, s[98:99]
	global_load_dwordx4 v[182:185], v[250:251], off
	s_mov_b32 s98, 0x2000
	s_mov_b32 s99, 0
	v_lshl_add_u64 v[250:251], v[246:247], 0, s[98:99]
	global_load_dwordx4 v[186:189], v[250:251], off
	v_lshl_add_u64 v[250:251], v[248:249], 0, s[98:99]
	global_load_dwordx4 v[190:193], v[250:251], off
	s_mov_b32 s98, 0x3000
	s_mov_b32 s99, 0
	v_lshl_add_u64 v[250:251], v[246:247], 0, s[98:99]
	global_load_dwordx4 v[194:197], v[250:251], off
	v_lshl_add_u64 v[250:251], v[248:249], 0, s[98:99]
	global_load_dwordx4 v[198:201], v[250:251], off
	s_mov_b32 s98, 0x8000
	s_mov_b32 s99, 0
	v_lshl_add_u64 v[250:251], v[246:247], 0, s[98:99]
	global_load_dwordx4 v[202:205], v[250:251], off
	v_lshl_add_u64 v[250:251], v[248:249], 0, s[98:99]
	global_load_dwordx4 v[226:229], v[250:251], off
	s_mov_b32 s98, 0x9000
	s_mov_b32 s99, 0
	v_lshl_add_u64 v[250:251], v[246:247], 0, s[98:99]
	global_load_dwordx4 v[230:233], v[250:251], off
	v_lshl_add_u64 v[250:251], v[248:249], 0, s[98:99]
	global_load_dwordx4 v[234:237], v[250:251], off
	s_mov_b32 s98, 0xa000
	s_mov_b32 s99, 0
	v_lshl_add_u64 v[250:251], v[246:247], 0, s[98:99]
	global_load_dwordx4 v[238:241], v[250:251], off
	v_lshl_add_u64 v[250:251], v[248:249], 0, s[98:99]
	global_load_dwordx4 v[242:245], v[250:251], off
	global_load_dwordx4 v[136:139], v[136:137], off
	s_add_i32 s51, 0, 0x20000
	global_load_dwordx4 v[140:143], v[140:141], off
	v_lshl_add_u64 v[166:167], v[164:165], 1, s[14:15]
	v_add_u32_e32 v146, s51, v144
	v_lshlrev_b64 v[144:145], 8, v[162:163]
	v_lshl_add_u64 v[170:171], v[166:167], 0, v[144:145]
	ds_read_b128 v[172:175], v146
	ds_read_b128 v[144:147], v146 offset:16
	s_cmp_lt_i32 s53, 4
	s_waitcnt lgkmcnt(0)
	v_mov_b32_e32 v176, v173
	v_mov_b32_e32 v177, v174
	v_mov_b32_e32 v173, v175
	v_pk_add_f32 v[172:173], v[176:177], v[172:173]
	s_nop 0
	v_add_f32_e32 v163, v172, v173
	v_fmamk_f32 v163, v163, 0x3c000000, v217
	v_cmp_gt_f32_e32 vcc, s92, v163
	v_mul_f32_e32 v165, 0x4f800000, v163
	s_nop 0
	v_cndmask_b32_e32 v163, v163, v165, vcc
	v_sqrt_f32_e32 v165, v163
	s_nop 0
	v_add_u32_e32 v172, -1, v165
	v_fma_f32 v173, -v172, v165, v163
	v_cmp_ge_f32_e64 s[6:7], 0, v173
	v_add_u32_e32 v173, 1, v165
	s_nop 0
	v_cndmask_b32_e64 v172, v165, v172, s[6:7]
	v_fma_f32 v165, -v173, v165, v163
	v_cmp_lt_f32_e64 s[6:7], 0, v165
	s_nop 1
	v_cndmask_b32_e64 v165, v172, v173, s[6:7]
	v_mul_f32_e32 v172, 0x37800000, v165
	v_cndmask_b32_e32 v165, v165, v172, vcc
	v_cmp_class_f32_e32 vcc, v163, v218
	s_nop 1
	v_cndmask_b32_e32 v163, v165, v163, vcc
	v_div_scale_f32 v165, s[0:1], v163, v163, 1.0
	v_rcp_f32_e32 v172, v165
	s_nop 0
	v_fma_f32 v173, -v165, v172, 1.0
	v_fmac_f32_e32 v172, v173, v172
	v_div_scale_f32 v173, vcc, 1.0, v163, 1.0
	v_mul_f32_e32 v174, v173, v172
	v_fma_f32 v175, -v165, v174, v173
	v_fmac_f32_e32 v174, v175, v172
	v_fma_f32 v165, -v165, v174, v173
	v_div_fmas_f32 v165, v165, v172, v174
	v_div_fixup_f32 v172, v165, v163, 1.0
	v_pk_mul_f32 v[128:129], v[128:129], v[172:173] op_sel_hi:[1,0]
	v_pk_mul_f32 v[130:131], v[130:131], v[172:173] op_sel_hi:[1,0]
	v_pk_mul_f32 v[134:135], v[134:135], v[172:173] op_sel_hi:[1,0]
	v_pk_mul_f32 v[132:133], v[132:133], v[172:173] op_sel_hi:[1,0]
	s_waitcnt vmcnt(0)
	v_pk_mul_f32 v[134:135], v[110:111], v[134:135]
	v_pk_mul_f32 v[130:131], v[106:107], v[130:131]
	v_pk_mul_f32 v[172:173], v[104:105], v[128:129]
	v_pk_mul_f32 v[174:175], v[108:109], v[132:133]
	v_pk_mul_f32 v[132:133], v[140:141], v[172:173]
	v_pk_mul_f32 v[128:129], v[142:143], v[130:131]
	v_pk_fma_f32 v[132:133], v[136:137], v[174:175], v[132:133] neg_lo:[0,0,1] neg_hi:[0,0,1]
	v_pk_fma_f32 v[128:129], v[138:139], v[134:135], v[128:129] neg_lo:[0,0,1] neg_hi:[0,0,1]
	v_pk_mul_f32 v[174:175], v[140:141], v[174:175]
	v_pk_mul_f32 v[134:135], v[142:143], v[134:135]
	s_nop 0
	v_pk_fma_f32 v[130:131], v[138:139], v[130:131], v[134:135]
	v_pk_fma_f32 v[134:135], v[136:137], v[172:173], v[174:175]
	v_cvt_pk_bf16_f32 v172, v132, v133
	v_cvt_pk_bf16_f32 v173, v128, v129
	v_cvt_pk_bf16_f32 v174, v134, v135
	v_cvt_pk_bf16_f32 v175, v130, v131
	global_store_dwordx2 v[170:171], v[172:173], off
	global_store_dwordx2 v[170:171], v[174:175], off offset:128
	v_mov_b32_e32 v172, v145
	v_mov_b32_e32 v173, v146
	v_mov_b32_e32 v145, v147
	v_pk_add_f32 v[144:145], v[172:173], v[144:145]
	s_nop 0
	v_add_f32_e32 v144, v144, v145
	v_fmamk_f32 v144, v144, 0x3c000000, v217
	v_cmp_gt_f32_e32 vcc, s92, v144
	v_mul_f32_e32 v145, 0x4f800000, v144
	s_nop 0
	v_cndmask_b32_e32 v144, v144, v145, vcc
	v_sqrt_f32_e32 v145, v144
	s_nop 0
	v_add_u32_e32 v146, -1, v145
	v_fma_f32 v147, -v146, v145, v144
	v_cmp_ge_f32_e64 s[6:7], 0, v147
	v_add_u32_e32 v147, 1, v145
	s_nop 0
	v_cndmask_b32_e64 v146, v145, v146, s[6:7]
	v_fma_f32 v145, -v147, v145, v144
	v_cmp_lt_f32_e64 s[6:7], 0, v145
	s_nop 1
	v_cndmask_b32_e64 v145, v146, v147, s[6:7]
	v_mul_f32_e32 v146, 0x37800000, v145
	v_cndmask_b32_e32 v145, v145, v146, vcc
	v_cmp_class_f32_e32 vcc, v144, v218
	s_nop 1
	v_cndmask_b32_e32 v144, v145, v144, vcc
	v_div_scale_f32 v145, s[0:1], v144, v144, 1.0
	v_rcp_f32_e32 v146, v145
	s_nop 0
	v_fma_f32 v147, -v145, v146, 1.0
	v_fmac_f32_e32 v146, v147, v146
	v_div_scale_f32 v147, vcc, 1.0, v144, 1.0
	v_mul_f32_e32 v163, v147, v146
	v_fma_f32 v165, -v145, v163, v147
	v_fmac_f32_e32 v163, v165, v146
	v_fma_f32 v145, -v145, v163, v147
	v_div_fmas_f32 v145, v145, v146, v163
	v_div_fixup_f32 v144, v145, v144, 1.0
	v_pk_mul_f32 v[122:123], v[122:123], v[144:145] op_sel_hi:[1,0]
	v_pk_mul_f32 v[126:127], v[126:127], v[144:145] op_sel_hi:[1,0]
	v_pk_mul_f32 v[124:125], v[124:125], v[144:145] op_sel_hi:[1,0]
	v_pk_mul_f32 v[120:121], v[120:121], v[144:145] op_sel_hi:[1,0]
	v_pk_mul_f32 v[122:123], v[106:107], v[122:123]
	v_pk_mul_f32 v[146:147], v[108:109], v[124:125]
	v_pk_mul_f32 v[126:127], v[110:111], v[126:127]
	v_pk_mul_f32 v[144:145], v[104:105], v[120:121]
	v_pk_mul_f32 v[120:121], v[142:143], v[122:123]
	v_pk_mul_f32 v[124:125], v[140:141], v[144:145]
	v_pk_fma_f32 v[120:121], v[138:139], v[126:127], v[120:121] neg_lo:[0,0,1] neg_hi:[0,0,1]
	v_pk_mul_f32 v[140:141], v[140:141], v[146:147]
	v_pk_mul_f32 v[126:127], v[142:143], v[126:127]
	v_pk_fma_f32 v[124:125], v[136:137], v[146:147], v[124:125] neg_lo:[0,0,1] neg_hi:[0,0,1]
	v_pk_fma_f32 v[122:123], v[138:139], v[122:123], v[126:127]
	v_pk_fma_f32 v[126:127], v[136:137], v[144:145], v[140:141]
	v_add_co_u32_e32 v140, vcc, s93, v170
	v_add_u32_e32 v144, 16, v162
	v_cvt_pk_bf16_f32 v136, v124, v125
	v_cvt_pk_bf16_f32 v137, v120, v121
	v_addc_co_u32_e32 v141, vcc, 0, v171, vcc
	v_ashrrev_i32_e32 v145, 31, v144
	v_cvt_pk_bf16_f32 v138, v126, v127
	v_cvt_pk_bf16_f32 v139, v122, v123
	global_store_dwordx2 v[140:141], v[136:137], off
	global_store_dwordx2 v[140:141], v[138:139], off offset:128
	v_lshlrev_b64 v[136:137], 6, v[144:145]
	v_lshl_add_u64 v[136:137], v[136:137], 0, s[64:65]
	v_lshlrev_b64 v[140:141], 2, v[136:137]
	v_lshl_add_u64 v[136:137], s[28:29], 0, v[140:141]
	v_lshl_add_u64 v[140:141], s[40:41], 0, v[140:141]
	v_lshl_add_u64 v[136:137], v[136:137], 0, v[168:169]
	v_lshl_add_u64 v[140:141], v[140:141], 0, v[168:169]
	v_mov_b64_e32 v[136:137], v[178:179]
	v_mov_b64_e32 v[138:139], v[180:181]
	v_lshl_add_u32 v163, v144, 5, s51
	v_mov_b64_e32 v[140:141], v[182:183]
	v_mov_b64_e32 v[142:143], v[184:185]
	s_mov_b32 s98, 0xb000
	s_mov_b32 s99, 0
	v_lshl_add_u64 v[250:251], v[246:247], 0, s[98:99]
	global_load_dwordx4 v[178:181], v[250:251], off
	v_lshl_add_u64 v[250:251], v[248:249], 0, s[98:99]
	global_load_dwordx4 v[182:185], v[250:251], off
	v_lshlrev_b64 v[144:145], 8, v[144:145]
	v_lshl_add_u64 v[174:175], v[166:167], 0, v[144:145]
	ds_read_b128 v[144:147], v163
	ds_read_b128 v[170:173], v163 offset:16
	s_waitcnt lgkmcnt(1)
	v_mov_b32_e32 v176, v145
	v_mov_b32_e32 v177, v146
	v_mov_b32_e32 v145, v147
	v_pk_add_f32 v[144:145], v[176:177], v[144:145]
	s_nop 0
	v_add_f32_e32 v144, v144, v145
	v_fmamk_f32 v144, v144, 0x3c000000, v217
	v_cmp_gt_f32_e32 vcc, s92, v144
	v_mul_f32_e32 v145, 0x4f800000, v144
	s_nop 0
	v_cndmask_b32_e32 v144, v144, v145, vcc
	v_sqrt_f32_e32 v145, v144
	s_nop 0
	v_add_u32_e32 v146, -1, v145
	v_fma_f32 v147, -v146, v145, v144
	v_cmp_ge_f32_e64 s[6:7], 0, v147
	v_add_u32_e32 v147, 1, v145
	s_nop 0
	v_cndmask_b32_e64 v146, v145, v146, s[6:7]
	v_fma_f32 v145, -v147, v145, v144
	v_cmp_lt_f32_e64 s[6:7], 0, v145
	s_nop 1
	v_cndmask_b32_e64 v145, v146, v147, s[6:7]
	v_mul_f32_e32 v146, 0x37800000, v145
	v_cndmask_b32_e32 v145, v145, v146, vcc
	v_cmp_class_f32_e32 vcc, v144, v218
	s_nop 1
	v_cndmask_b32_e32 v144, v145, v144, vcc
	v_div_scale_f32 v145, s[0:1], v144, v144, 1.0
	v_rcp_f32_e32 v146, v145
	s_nop 0
	v_fma_f32 v147, -v145, v146, 1.0
	v_fmac_f32_e32 v146, v147, v146
	v_div_scale_f32 v147, vcc, 1.0, v144, 1.0
	v_mul_f32_e32 v163, v147, v146
	v_fma_f32 v165, -v145, v163, v147
	v_fmac_f32_e32 v163, v165, v146
	v_fma_f32 v145, -v145, v163, v147
	v_div_fmas_f32 v145, v145, v146, v163
	v_div_fixup_f32 v144, v145, v144, 1.0
	v_pk_mul_f32 v[112:113], v[112:113], v[144:145] op_sel_hi:[1,0]
	v_pk_mul_f32 v[114:115], v[114:115], v[144:145] op_sel_hi:[1,0]
	v_pk_mul_f32 v[118:119], v[118:119], v[144:145] op_sel_hi:[1,0]
	v_pk_mul_f32 v[116:117], v[116:117], v[144:145] op_sel_hi:[1,0]
	v_pk_mul_f32 v[114:115], v[106:107], v[114:115]
	v_pk_mul_f32 v[144:145], v[104:105], v[112:113]
	v_pk_mul_f32 v[146:147], v[108:109], v[116:117]
	v_pk_mul_f32 v[118:119], v[110:111], v[118:119]
	s_nop 0
	v_pk_mul_f32 v[116:117], v[140:141], v[144:145]
	v_pk_mul_f32 v[112:113], v[142:143], v[114:115]
	v_pk_fma_f32 v[116:117], v[136:137], v[146:147], v[116:117] neg_lo:[0,0,1] neg_hi:[0,0,1]
	v_pk_fma_f32 v[112:113], v[138:139], v[118:119], v[112:113] neg_lo:[0,0,1] neg_hi:[0,0,1]
	v_pk_mul_f32 v[146:147], v[140:141], v[146:147]
	v_pk_mul_f32 v[118:119], v[142:143], v[118:119]
	s_nop 0
	v_pk_fma_f32 v[114:115], v[138:139], v[114:115], v[118:119]
	v_pk_fma_f32 v[118:119], v[136:137], v[144:145], v[146:147]
	v_cvt_pk_bf16_f32 v144, v116, v117
	v_cvt_pk_bf16_f32 v145, v112, v113
	v_cvt_pk_bf16_f32 v146, v118, v119
	v_cvt_pk_bf16_f32 v147, v114, v115
	global_store_dwordx2 v[174:175], v[144:145], off
	global_store_dwordx2 v[174:175], v[146:147], off offset:128
	s_waitcnt lgkmcnt(0)
	v_mov_b32_e32 v144, v171
	v_mov_b32_e32 v145, v172
	v_mov_b32_e32 v171, v173
	v_pk_add_f32 v[144:145], v[144:145], v[170:171]
	s_nop 0
	v_add_f32_e32 v144, v144, v145
	v_fmamk_f32 v144, v144, 0x3c000000, v217
	v_cmp_gt_f32_e32 vcc, s92, v144
	v_mul_f32_e32 v145, 0x4f800000, v144
	s_nop 0
	v_cndmask_b32_e32 v144, v144, v145, vcc
	v_sqrt_f32_e32 v145, v144
	s_nop 0
	v_add_u32_e32 v146, -1, v145
	v_fma_f32 v147, -v146, v145, v144
	v_cmp_ge_f32_e64 s[6:7], 0, v147
	v_add_u32_e32 v147, 1, v145
	s_nop 0
	v_cndmask_b32_e64 v146, v145, v146, s[6:7]
	v_fma_f32 v145, -v147, v145, v144
	v_cmp_lt_f32_e64 s[6:7], 0, v145
	s_nop 1
	v_cndmask_b32_e64 v145, v146, v147, s[6:7]
	v_mul_f32_e32 v146, 0x37800000, v145
	v_cndmask_b32_e32 v145, v145, v146, vcc
	v_cmp_class_f32_e32 vcc, v144, v218
	s_nop 1
	v_cndmask_b32_e32 v144, v145, v144, vcc
	v_div_scale_f32 v145, s[0:1], v144, v144, 1.0
	v_rcp_f32_e32 v146, v145
	s_nop 0
	v_fma_f32 v147, -v145, v146, 1.0
	v_fmac_f32_e32 v146, v147, v146
	v_div_scale_f32 v147, vcc, 1.0, v144, 1.0
	v_mul_f32_e32 v163, v147, v146
	v_fma_f32 v165, -v145, v163, v147
	v_fmac_f32_e32 v163, v165, v146
	v_fma_f32 v145, -v145, v163, v147
	v_div_fmas_f32 v145, v145, v146, v163
	v_div_fixup_f32 v144, v145, v144, 1.0
	v_pk_mul_f32 v[98:99], v[98:99], v[144:145] op_sel_hi:[1,0]
	v_pk_mul_f32 v[102:103], v[102:103], v[144:145] op_sel_hi:[1,0]
	v_pk_mul_f32 v[100:101], v[100:101], v[144:145] op_sel_hi:[1,0]
	v_pk_mul_f32 v[96:97], v[96:97], v[144:145] op_sel_hi:[1,0]
	v_pk_mul_f32 v[98:99], v[106:107], v[98:99]
	v_pk_mul_f32 v[146:147], v[108:109], v[100:101]
	v_pk_mul_f32 v[102:103], v[110:111], v[102:103]
	v_pk_mul_f32 v[144:145], v[104:105], v[96:97]
	v_pk_mul_f32 v[96:97], v[142:143], v[98:99]
	v_pk_mul_f32 v[100:101], v[140:141], v[144:145]
	v_pk_fma_f32 v[96:97], v[138:139], v[102:103], v[96:97] neg_lo:[0,0,1] neg_hi:[0,0,1]
	v_pk_mul_f32 v[140:141], v[140:141], v[146:147]
	v_pk_mul_f32 v[102:103], v[142:143], v[102:103]
	v_pk_fma_f32 v[100:101], v[136:137], v[146:147], v[100:101] neg_lo:[0,0,1] neg_hi:[0,0,1]
	v_pk_fma_f32 v[98:99], v[138:139], v[98:99], v[102:103]
	v_pk_fma_f32 v[102:103], v[136:137], v[144:145], v[140:141]
	v_add_co_u32_e32 v140, vcc, s93, v174
	v_add_u32_e32 v144, 32, v162
	v_cvt_pk_bf16_f32 v136, v100, v101
	v_cvt_pk_bf16_f32 v137, v96, v97
	v_addc_co_u32_e32 v141, vcc, 0, v175, vcc
	v_ashrrev_i32_e32 v145, 31, v144
	v_cvt_pk_bf16_f32 v138, v102, v103
	v_cvt_pk_bf16_f32 v139, v98, v99
	global_store_dwordx2 v[140:141], v[136:137], off
	global_store_dwordx2 v[140:141], v[138:139], off offset:128
	v_lshlrev_b64 v[136:137], 6, v[144:145]
	v_lshl_add_u64 v[136:137], v[136:137], 0, s[64:65]
	v_lshlrev_b64 v[140:141], 2, v[136:137]
	v_lshl_add_u64 v[136:137], s[28:29], 0, v[140:141]
	v_lshl_add_u64 v[140:141], s[40:41], 0, v[140:141]
	v_lshl_add_u64 v[136:137], v[136:137], 0, v[168:169]
	v_lshl_add_u64 v[140:141], v[140:141], 0, v[168:169]
	v_mov_b64_e32 v[136:137], v[186:187]
	v_mov_b64_e32 v[138:139], v[188:189]
	v_lshl_add_u32 v163, v144, 5, s51
	v_mov_b64_e32 v[140:141], v[190:191]
	v_mov_b64_e32 v[142:143], v[192:193]
	v_lshlrev_b64 v[144:145], 8, v[144:145]
	v_lshl_add_u64 v[174:175], v[166:167], 0, v[144:145]
	ds_read_b128 v[144:147], v163
	ds_read_b128 v[170:173], v163 offset:16
	s_waitcnt lgkmcnt(1)
	v_mov_b32_e32 v176, v145
	v_mov_b32_e32 v177, v146
	v_mov_b32_e32 v145, v147
	v_pk_add_f32 v[144:145], v[176:177], v[144:145]
	s_nop 0
	v_add_f32_e32 v144, v144, v145
	v_fmamk_f32 v144, v144, 0x3c000000, v217
	v_cmp_gt_f32_e32 vcc, s92, v144
	v_mul_f32_e32 v145, 0x4f800000, v144
	s_nop 0
	v_cndmask_b32_e32 v144, v144, v145, vcc
	v_sqrt_f32_e32 v145, v144
	s_nop 0
	v_add_u32_e32 v146, -1, v145
	v_fma_f32 v147, -v146, v145, v144
	v_cmp_ge_f32_e64 s[6:7], 0, v147
	v_add_u32_e32 v147, 1, v145
	s_nop 0
	v_cndmask_b32_e64 v146, v145, v146, s[6:7]
	v_fma_f32 v145, -v147, v145, v144
	v_cmp_lt_f32_e64 s[6:7], 0, v145
	s_nop 1
	v_cndmask_b32_e64 v145, v146, v147, s[6:7]
	v_mul_f32_e32 v146, 0x37800000, v145
	v_cndmask_b32_e32 v145, v145, v146, vcc
	v_cmp_class_f32_e32 vcc, v144, v218
	s_nop 1
	v_cndmask_b32_e32 v144, v145, v144, vcc
	v_div_scale_f32 v145, s[0:1], v144, v144, 1.0
	v_rcp_f32_e32 v146, v145
	s_nop 0
	v_fma_f32 v147, -v145, v146, 1.0
	v_fmac_f32_e32 v146, v147, v146
	v_div_scale_f32 v147, vcc, 1.0, v144, 1.0
	v_mul_f32_e32 v163, v147, v146
	v_fma_f32 v165, -v145, v163, v147
	v_fmac_f32_e32 v163, v165, v146
	v_fma_f32 v145, -v145, v163, v147
	v_div_fmas_f32 v145, v145, v146, v163
	v_div_fixup_f32 v144, v145, v144, 1.0
	v_pk_mul_f32 v[88:89], v[88:89], v[144:145] op_sel_hi:[1,0]
	v_pk_mul_f32 v[90:91], v[90:91], v[144:145] op_sel_hi:[1,0]
	v_pk_mul_f32 v[94:95], v[94:95], v[144:145] op_sel_hi:[1,0]
	v_pk_mul_f32 v[92:93], v[92:93], v[144:145] op_sel_hi:[1,0]
	v_pk_mul_f32 v[144:145], v[106:107], v[90:91]
	v_pk_mul_f32 v[176:177], v[104:105], v[88:89]
	v_pk_mul_f32 v[146:147], v[108:109], v[92:93]
	v_pk_mul_f32 v[94:95], v[110:111], v[94:95]
	s_nop 0
	v_pk_mul_f32 v[88:89], v[140:141], v[176:177]
	v_pk_mul_f32 v[90:91], v[142:143], v[144:145]
	v_pk_fma_f32 v[92:93], v[136:137], v[146:147], v[88:89] neg_lo:[0,0,1] neg_hi:[0,0,1]
	v_pk_fma_f32 v[90:91], v[138:139], v[94:95], v[90:91] neg_lo:[0,0,1] neg_hi:[0,0,1]
	v_pk_mul_f32 v[146:147], v[140:141], v[146:147]
	v_pk_mul_f32 v[88:89], v[142:143], v[94:95]
	v_pk_fma_f32 v[94:95], v[136:137], v[176:177], v[146:147]
	v_pk_fma_f32 v[88:89], v[138:139], v[144:145], v[88:89]
	v_cvt_pk_bf16_f32 v144, v92, v93
	v_cvt_pk_bf16_f32 v145, v90, v91
	v_cvt_pk_bf16_f32 v146, v94, v95
	v_cvt_pk_bf16_f32 v147, v88, v89
	global_store_dwordx2 v[174:175], v[144:145], off
	global_store_dwordx2 v[174:175], v[146:147], off offset:128
	s_waitcnt lgkmcnt(0)
	v_mov_b32_e32 v144, v171
	v_mov_b32_e32 v145, v172
	v_mov_b32_e32 v171, v173
	v_pk_add_f32 v[144:145], v[144:145], v[170:171]
	s_nop 0
	v_add_f32_e32 v144, v144, v145
	v_fmamk_f32 v144, v144, 0x3c000000, v217
	v_cmp_gt_f32_e32 vcc, s92, v144
	v_mul_f32_e32 v145, 0x4f800000, v144
	s_nop 0
	v_cndmask_b32_e32 v144, v144, v145, vcc
	v_sqrt_f32_e32 v145, v144
	s_nop 0
	v_add_u32_e32 v146, -1, v145
	v_fma_f32 v147, -v146, v145, v144
	v_cmp_ge_f32_e64 s[6:7], 0, v147
	v_add_u32_e32 v147, 1, v145
	s_nop 0
	v_cndmask_b32_e64 v146, v145, v146, s[6:7]
	v_fma_f32 v145, -v147, v145, v144
	v_cmp_lt_f32_e64 s[6:7], 0, v145
	s_nop 1
	v_cndmask_b32_e64 v145, v146, v147, s[6:7]
	v_mul_f32_e32 v146, 0x37800000, v145
	v_cndmask_b32_e32 v145, v145, v146, vcc
	v_cmp_class_f32_e32 vcc, v144, v218
	s_nop 1
	v_cndmask_b32_e32 v144, v145, v144, vcc
	v_div_scale_f32 v145, s[0:1], v144, v144, 1.0
	v_rcp_f32_e32 v146, v145
	s_nop 0
	v_fma_f32 v147, -v145, v146, 1.0
	v_fmac_f32_e32 v146, v147, v146
	v_div_scale_f32 v147, vcc, 1.0, v144, 1.0
	v_mul_f32_e32 v163, v147, v146
	v_fma_f32 v165, -v145, v163, v147
	v_fmac_f32_e32 v163, v165, v146
	v_fma_f32 v145, -v145, v163, v147
	v_div_fmas_f32 v145, v145, v146, v163
	v_div_fixup_f32 v144, v145, v144, 1.0
	v_pk_mul_f32 v[80:81], v[80:81], v[144:145] op_sel_hi:[1,0]
	v_pk_mul_f32 v[86:87], v[86:87], v[144:145] op_sel_hi:[1,0]
	v_pk_mul_f32 v[84:85], v[84:85], v[144:145] op_sel_hi:[1,0]
	v_pk_mul_f32 v[82:83], v[82:83], v[144:145] op_sel_hi:[1,0]
	v_pk_mul_f32 v[170:171], v[104:105], v[80:81]
	v_pk_mul_f32 v[146:147], v[108:109], v[84:85]
	v_pk_mul_f32 v[86:87], v[110:111], v[86:87]
	v_pk_mul_f32 v[144:145], v[106:107], v[82:83]
	v_pk_mul_f32 v[80:81], v[140:141], v[170:171]
	v_pk_mul_f32 v[82:83], v[142:143], v[144:145]
	v_pk_fma_f32 v[84:85], v[136:137], v[146:147], v[80:81] neg_lo:[0,0,1] neg_hi:[0,0,1]
	v_pk_mul_f32 v[140:141], v[140:141], v[146:147]
	v_pk_mul_f32 v[80:81], v[142:143], v[86:87]
	v_pk_fma_f32 v[82:83], v[138:139], v[86:87], v[82:83] neg_lo:[0,0,1] neg_hi:[0,0,1]
	v_pk_fma_f32 v[80:81], v[138:139], v[144:145], v[80:81]
	v_pk_fma_f32 v[86:87], v[136:137], v[170:171], v[140:141]
	v_add_co_u32_e32 v140, vcc, s93, v174
	v_add_u32_e32 v144, 48, v162
	v_cvt_pk_bf16_f32 v136, v84, v85
	v_cvt_pk_bf16_f32 v137, v82, v83
	v_addc_co_u32_e32 v141, vcc, 0, v175, vcc
	v_ashrrev_i32_e32 v145, 31, v144
	v_cvt_pk_bf16_f32 v138, v86, v87
	v_cvt_pk_bf16_f32 v139, v80, v81
	global_store_dwordx2 v[140:141], v[136:137], off
	global_store_dwordx2 v[140:141], v[138:139], off offset:128
	v_lshlrev_b64 v[136:137], 6, v[144:145]
	v_lshl_add_u64 v[136:137], v[136:137], 0, s[64:65]
	v_lshlrev_b64 v[140:141], 2, v[136:137]
	v_lshl_add_u64 v[136:137], s[28:29], 0, v[140:141]
	v_lshl_add_u64 v[140:141], s[40:41], 0, v[140:141]
	v_lshl_add_u64 v[136:137], v[136:137], 0, v[168:169]
	v_lshl_add_u64 v[140:141], v[140:141], 0, v[168:169]
	v_mov_b64_e32 v[136:137], v[194:195]
	v_mov_b64_e32 v[138:139], v[196:197]
	v_lshl_add_u32 v163, v144, 5, s51
	v_mov_b64_e32 v[140:141], v[198:199]
	v_mov_b64_e32 v[142:143], v[200:201]
	v_lshlrev_b64 v[144:145], 8, v[144:145]
	v_lshl_add_u64 v[174:175], v[166:167], 0, v[144:145]
	ds_read_b128 v[144:147], v163
	ds_read_b128 v[170:173], v163 offset:16
	s_waitcnt lgkmcnt(1)
	v_mov_b32_e32 v176, v145
	v_mov_b32_e32 v177, v146
	v_mov_b32_e32 v145, v147
	v_pk_add_f32 v[144:145], v[176:177], v[144:145]
	s_nop 0
	v_add_f32_e32 v144, v144, v145
	v_fmamk_f32 v144, v144, 0x3c000000, v217
	v_cmp_gt_f32_e32 vcc, s92, v144
	v_mul_f32_e32 v145, 0x4f800000, v144
	s_nop 0
	v_cndmask_b32_e32 v144, v144, v145, vcc
	v_sqrt_f32_e32 v145, v144
	s_nop 0
	v_add_u32_e32 v146, -1, v145
	v_fma_f32 v147, -v146, v145, v144
	v_cmp_ge_f32_e64 s[6:7], 0, v147
	v_add_u32_e32 v147, 1, v145
	s_nop 0
	v_cndmask_b32_e64 v146, v145, v146, s[6:7]
	v_fma_f32 v145, -v147, v145, v144
	v_cmp_lt_f32_e64 s[6:7], 0, v145
	s_nop 1
	v_cndmask_b32_e64 v145, v146, v147, s[6:7]
	v_mul_f32_e32 v146, 0x37800000, v145
	v_cndmask_b32_e32 v145, v145, v146, vcc
	v_cmp_class_f32_e32 vcc, v144, v218
	s_nop 1
	v_cndmask_b32_e32 v144, v145, v144, vcc
	v_div_scale_f32 v145, s[0:1], v144, v144, 1.0
	v_rcp_f32_e32 v146, v145
	s_nop 0
	v_fma_f32 v147, -v145, v146, 1.0
	v_fmac_f32_e32 v146, v147, v146
	v_div_scale_f32 v147, vcc, 1.0, v144, 1.0
	v_mul_f32_e32 v163, v147, v146
	v_fma_f32 v165, -v145, v163, v147
	v_fmac_f32_e32 v163, v165, v146
	v_fma_f32 v145, -v145, v163, v147
	v_div_fmas_f32 v145, v145, v146, v163
	v_div_fixup_f32 v144, v145, v144, 1.0
	v_pk_mul_f32 v[72:73], v[72:73], v[144:145] op_sel_hi:[1,0]
	v_pk_mul_f32 v[74:75], v[74:75], v[144:145] op_sel_hi:[1,0]
	v_pk_mul_f32 v[78:79], v[78:79], v[144:145] op_sel_hi:[1,0]
	v_pk_mul_f32 v[76:77], v[76:77], v[144:145] op_sel_hi:[1,0]
	v_pk_mul_f32 v[74:75], v[106:107], v[74:75]
	v_pk_mul_f32 v[144:145], v[104:105], v[72:73]
	v_pk_mul_f32 v[146:147], v[108:109], v[76:77]
	v_pk_mul_f32 v[78:79], v[110:111], v[78:79]
	s_nop 0
	v_pk_mul_f32 v[76:77], v[140:141], v[144:145]
	v_pk_mul_f32 v[72:73], v[142:143], v[74:75]
	v_pk_fma_f32 v[76:77], v[136:137], v[146:147], v[76:77] neg_lo:[0,0,1] neg_hi:[0,0,1]
	v_pk_fma_f32 v[72:73], v[138:139], v[78:79], v[72:73] neg_lo:[0,0,1] neg_hi:[0,0,1]
	v_pk_mul_f32 v[146:147], v[140:141], v[146:147]
	v_pk_mul_f32 v[78:79], v[142:143], v[78:79]
	s_nop 0
	v_pk_fma_f32 v[74:75], v[138:139], v[74:75], v[78:79]
	v_pk_fma_f32 v[78:79], v[136:137], v[144:145], v[146:147]
	v_cvt_pk_bf16_f32 v144, v76, v77
	v_cvt_pk_bf16_f32 v145, v72, v73
	v_cvt_pk_bf16_f32 v146, v78, v79
	v_cvt_pk_bf16_f32 v147, v74, v75
	global_store_dwordx2 v[174:175], v[144:145], off
	global_store_dwordx2 v[174:175], v[146:147], off offset:128
	s_waitcnt lgkmcnt(0)
	v_mov_b32_e32 v144, v171
	v_mov_b32_e32 v145, v172
	v_mov_b32_e32 v171, v173
	v_pk_add_f32 v[144:145], v[144:145], v[170:171]
	s_nop 0
	v_add_f32_e32 v144, v144, v145
	v_fmamk_f32 v144, v144, 0x3c000000, v217
	v_cmp_gt_f32_e32 vcc, s92, v144
	v_mul_f32_e32 v145, 0x4f800000, v144
	s_nop 0
	v_cndmask_b32_e32 v144, v144, v145, vcc
	v_sqrt_f32_e32 v145, v144
	s_nop 0
	v_add_u32_e32 v146, -1, v145
	v_fma_f32 v147, -v146, v145, v144
	v_cmp_ge_f32_e64 s[6:7], 0, v147
	v_add_u32_e32 v147, 1, v145
	s_nop 0
	v_cndmask_b32_e64 v146, v145, v146, s[6:7]
	v_fma_f32 v145, -v147, v145, v144
	v_cmp_lt_f32_e64 s[6:7], 0, v145
	s_nop 1
	v_cndmask_b32_e64 v145, v146, v147, s[6:7]
	v_mul_f32_e32 v146, 0x37800000, v145
	v_cndmask_b32_e32 v145, v145, v146, vcc
	v_cmp_class_f32_e32 vcc, v144, v218
	s_nop 1
	v_cndmask_b32_e32 v144, v145, v144, vcc
	v_div_scale_f32 v145, s[0:1], v144, v144, 1.0
	v_rcp_f32_e32 v146, v145
	s_nop 0
	v_fma_f32 v147, -v145, v146, 1.0
	v_fmac_f32_e32 v146, v147, v146
	v_div_scale_f32 v147, vcc, 1.0, v144, 1.0
	v_mul_f32_e32 v163, v147, v146
	v_fma_f32 v165, -v145, v163, v147
	v_fmac_f32_e32 v163, v165, v146
	v_fma_f32 v145, -v145, v163, v147
	v_div_fmas_f32 v145, v145, v146, v163
	v_div_fixup_f32 v144, v145, v144, 1.0
	v_pk_mul_f32 v[66:67], v[66:67], v[144:145] op_sel_hi:[1,0]
	v_pk_mul_f32 v[70:71], v[70:71], v[144:145] op_sel_hi:[1,0]
	v_pk_mul_f32 v[68:69], v[68:69], v[144:145] op_sel_hi:[1,0]
	v_pk_mul_f32 v[64:65], v[64:65], v[144:145] op_sel_hi:[1,0]
	v_pk_mul_f32 v[66:67], v[106:107], v[66:67]
	v_pk_mul_f32 v[146:147], v[108:109], v[68:69]
	v_pk_mul_f32 v[70:71], v[110:111], v[70:71]
	v_pk_mul_f32 v[144:145], v[104:105], v[64:65]
	v_pk_mul_f32 v[64:65], v[142:143], v[66:67]
	v_pk_mul_f32 v[68:69], v[140:141], v[144:145]
	v_pk_fma_f32 v[64:65], v[138:139], v[70:71], v[64:65] neg_lo:[0,0,1] neg_hi:[0,0,1]
	v_pk_mul_f32 v[140:141], v[140:141], v[146:147]
	v_pk_mul_f32 v[70:71], v[142:143], v[70:71]
	v_pk_fma_f32 v[68:69], v[136:137], v[146:147], v[68:69] neg_lo:[0,0,1] neg_hi:[0,0,1]
	v_pk_fma_f32 v[66:67], v[138:139], v[66:67], v[70:71]
	v_pk_fma_f32 v[70:71], v[136:137], v[144:145], v[140:141]
	v_add_co_u32_e32 v140, vcc, s93, v174
	v_add_u32_e32 v144, 0x80, v162
	v_cvt_pk_bf16_f32 v136, v68, v69
	v_cvt_pk_bf16_f32 v137, v64, v65
	v_addc_co_u32_e32 v141, vcc, 0, v175, vcc
	v_ashrrev_i32_e32 v145, 31, v144
	v_cvt_pk_bf16_f32 v138, v70, v71
	v_cvt_pk_bf16_f32 v139, v66, v67
	global_store_dwordx2 v[140:141], v[136:137], off
	global_store_dwordx2 v[140:141], v[138:139], off offset:128
	v_lshlrev_b64 v[136:137], 6, v[144:145]
	v_lshl_add_u64 v[136:137], v[136:137], 0, s[64:65]
	v_lshlrev_b64 v[140:141], 2, v[136:137]
	v_lshl_add_u64 v[136:137], s[28:29], 0, v[140:141]
	v_lshl_add_u64 v[140:141], s[40:41], 0, v[140:141]
	v_lshl_add_u64 v[136:137], v[136:137], 0, v[168:169]
	v_lshl_add_u64 v[140:141], v[140:141], 0, v[168:169]
	v_mov_b64_e32 v[136:137], v[202:203]
	v_mov_b64_e32 v[138:139], v[204:205]
	v_lshl_add_u32 v163, v144, 5, s51
	v_mov_b64_e32 v[140:141], v[226:227]
	v_mov_b64_e32 v[142:143], v[228:229]
	v_lshlrev_b64 v[144:145], 8, v[144:145]
	v_lshl_add_u64 v[174:175], v[166:167], 0, v[144:145]
	ds_read_b128 v[144:147], v163
	ds_read_b128 v[170:173], v163 offset:16
	s_waitcnt lgkmcnt(1)
	v_mov_b32_e32 v176, v145
	v_mov_b32_e32 v177, v146
	v_mov_b32_e32 v145, v147
	v_pk_add_f32 v[144:145], v[176:177], v[144:145]
	s_nop 0
	v_add_f32_e32 v144, v144, v145
	v_fmamk_f32 v144, v144, 0x3c000000, v217
	v_cmp_gt_f32_e32 vcc, s92, v144
	v_mul_f32_e32 v145, 0x4f800000, v144
	s_nop 0
	v_cndmask_b32_e32 v144, v144, v145, vcc
	v_sqrt_f32_e32 v145, v144
	s_nop 0
	v_add_u32_e32 v146, -1, v145
	v_fma_f32 v147, -v146, v145, v144
	v_cmp_ge_f32_e64 s[6:7], 0, v147
	v_add_u32_e32 v147, 1, v145
	s_nop 0
	v_cndmask_b32_e64 v146, v145, v146, s[6:7]
	v_fma_f32 v145, -v147, v145, v144
	v_cmp_lt_f32_e64 s[6:7], 0, v145
	s_nop 1
	v_cndmask_b32_e64 v145, v146, v147, s[6:7]
	v_mul_f32_e32 v146, 0x37800000, v145
	v_cndmask_b32_e32 v145, v145, v146, vcc
	v_cmp_class_f32_e32 vcc, v144, v218
	s_nop 1
	v_cndmask_b32_e32 v144, v145, v144, vcc
	v_div_scale_f32 v145, s[0:1], v144, v144, 1.0
	v_rcp_f32_e32 v146, v145
	s_nop 0
	v_fma_f32 v147, -v145, v146, 1.0
	v_fmac_f32_e32 v146, v147, v146
	v_div_scale_f32 v147, vcc, 1.0, v144, 1.0
	v_mul_f32_e32 v163, v147, v146
	v_fma_f32 v165, -v145, v163, v147
	v_fmac_f32_e32 v163, v165, v146
	v_fma_f32 v145, -v145, v163, v147
	v_div_fmas_f32 v145, v145, v146, v163
	v_div_fixup_f32 v144, v145, v144, 1.0
	v_pk_mul_f32 v[56:57], v[56:57], v[144:145] op_sel_hi:[1,0]
	v_pk_mul_f32 v[58:59], v[58:59], v[144:145] op_sel_hi:[1,0]
	v_pk_mul_f32 v[62:63], v[62:63], v[144:145] op_sel_hi:[1,0]
	v_pk_mul_f32 v[60:61], v[60:61], v[144:145] op_sel_hi:[1,0]
	v_pk_mul_f32 v[58:59], v[106:107], v[58:59]
	v_pk_mul_f32 v[144:145], v[104:105], v[56:57]
	v_pk_mul_f32 v[146:147], v[108:109], v[60:61]
	v_pk_mul_f32 v[62:63], v[110:111], v[62:63]
	s_nop 0
	v_pk_mul_f32 v[60:61], v[140:141], v[144:145]
	v_pk_mul_f32 v[56:57], v[142:143], v[58:59]
	v_pk_fma_f32 v[60:61], v[136:137], v[146:147], v[60:61] neg_lo:[0,0,1] neg_hi:[0,0,1]
	v_pk_fma_f32 v[56:57], v[138:139], v[62:63], v[56:57] neg_lo:[0,0,1] neg_hi:[0,0,1]
	v_pk_mul_f32 v[146:147], v[140:141], v[146:147]
	v_pk_mul_f32 v[62:63], v[142:143], v[62:63]
	s_nop 0
	v_pk_fma_f32 v[58:59], v[138:139], v[58:59], v[62:63]
	v_pk_fma_f32 v[62:63], v[136:137], v[144:145], v[146:147]
	v_cvt_pk_bf16_f32 v144, v60, v61
	v_cvt_pk_bf16_f32 v145, v56, v57
	v_cvt_pk_bf16_f32 v146, v62, v63
	v_cvt_pk_bf16_f32 v147, v58, v59
	global_store_dwordx2 v[174:175], v[144:145], off
	global_store_dwordx2 v[174:175], v[146:147], off offset:128
	s_waitcnt lgkmcnt(0)
	v_mov_b32_e32 v144, v171
	v_mov_b32_e32 v145, v172
	v_mov_b32_e32 v171, v173
	v_pk_add_f32 v[144:145], v[144:145], v[170:171]
	s_nop 0
	v_add_f32_e32 v144, v144, v145
	v_fmamk_f32 v144, v144, 0x3c000000, v217
	v_cmp_gt_f32_e32 vcc, s92, v144
	v_mul_f32_e32 v145, 0x4f800000, v144
	s_nop 0
	v_cndmask_b32_e32 v144, v144, v145, vcc
	v_sqrt_f32_e32 v145, v144
	s_nop 0
	v_add_u32_e32 v146, -1, v145
	v_fma_f32 v147, -v146, v145, v144
	v_cmp_ge_f32_e64 s[6:7], 0, v147
	v_add_u32_e32 v147, 1, v145
	s_nop 0
	v_cndmask_b32_e64 v146, v145, v146, s[6:7]
	v_fma_f32 v145, -v147, v145, v144
	v_cmp_lt_f32_e64 s[6:7], 0, v145
	s_nop 1
	v_cndmask_b32_e64 v145, v146, v147, s[6:7]
	v_mul_f32_e32 v146, 0x37800000, v145
	v_cndmask_b32_e32 v145, v145, v146, vcc
	v_cmp_class_f32_e32 vcc, v144, v218
	s_nop 1
	v_cndmask_b32_e32 v144, v145, v144, vcc
	v_div_scale_f32 v145, s[0:1], v144, v144, 1.0
	v_rcp_f32_e32 v146, v145
	s_nop 0
	v_fma_f32 v147, -v145, v146, 1.0
	v_fmac_f32_e32 v146, v147, v146
	v_div_scale_f32 v147, vcc, 1.0, v144, 1.0
	v_mul_f32_e32 v163, v147, v146
	v_fma_f32 v165, -v145, v163, v147
	v_fmac_f32_e32 v163, v165, v146
	v_fma_f32 v145, -v145, v163, v147
	v_div_fmas_f32 v145, v145, v146, v163
	v_div_fixup_f32 v144, v145, v144, 1.0
	v_pk_mul_f32 v[50:51], v[50:51], v[144:145] op_sel_hi:[1,0]
	v_pk_mul_f32 v[54:55], v[54:55], v[144:145] op_sel_hi:[1,0]
	v_pk_mul_f32 v[52:53], v[52:53], v[144:145] op_sel_hi:[1,0]
	v_pk_mul_f32 v[48:49], v[48:49], v[144:145] op_sel_hi:[1,0]
	v_pk_mul_f32 v[50:51], v[106:107], v[50:51]
	v_pk_mul_f32 v[146:147], v[108:109], v[52:53]
	v_pk_mul_f32 v[54:55], v[110:111], v[54:55]
	v_pk_mul_f32 v[144:145], v[104:105], v[48:49]
	v_pk_mul_f32 v[48:49], v[142:143], v[50:51]
	v_pk_mul_f32 v[52:53], v[140:141], v[144:145]
	v_pk_fma_f32 v[48:49], v[138:139], v[54:55], v[48:49] neg_lo:[0,0,1] neg_hi:[0,0,1]
	v_pk_mul_f32 v[140:141], v[140:141], v[146:147]
	v_pk_mul_f32 v[54:55], v[142:143], v[54:55]
	v_pk_fma_f32 v[52:53], v[136:137], v[146:147], v[52:53] neg_lo:[0,0,1] neg_hi:[0,0,1]
	v_pk_fma_f32 v[50:51], v[138:139], v[50:51], v[54:55]
	v_pk_fma_f32 v[54:55], v[136:137], v[144:145], v[140:141]
	v_add_co_u32_e32 v140, vcc, s93, v174
	v_add_u32_e32 v144, 0x90, v162
	v_cvt_pk_bf16_f32 v136, v52, v53
	v_cvt_pk_bf16_f32 v137, v48, v49
	v_addc_co_u32_e32 v141, vcc, 0, v175, vcc
	v_ashrrev_i32_e32 v145, 31, v144
	v_cvt_pk_bf16_f32 v138, v54, v55
	v_cvt_pk_bf16_f32 v139, v50, v51
	global_store_dwordx2 v[140:141], v[136:137], off
	global_store_dwordx2 v[140:141], v[138:139], off offset:128
	v_lshlrev_b64 v[136:137], 6, v[144:145]
	v_lshl_add_u64 v[136:137], v[136:137], 0, s[64:65]
	v_lshlrev_b64 v[140:141], 2, v[136:137]
	v_lshl_add_u64 v[136:137], s[28:29], 0, v[140:141]
	v_lshl_add_u64 v[140:141], s[40:41], 0, v[140:141]
	v_lshl_add_u64 v[136:137], v[136:137], 0, v[168:169]
	v_lshl_add_u64 v[140:141], v[140:141], 0, v[168:169]
	v_mov_b64_e32 v[136:137], v[230:231]
	v_mov_b64_e32 v[138:139], v[232:233]
	v_lshl_add_u32 v163, v144, 5, s51
	v_mov_b64_e32 v[140:141], v[234:235]
	v_mov_b64_e32 v[142:143], v[236:237]
	v_lshlrev_b64 v[144:145], 8, v[144:145]
	v_lshl_add_u64 v[174:175], v[166:167], 0, v[144:145]
	ds_read_b128 v[144:147], v163
	ds_read_b128 v[170:173], v163 offset:16
	s_waitcnt lgkmcnt(1)
	v_mov_b32_e32 v176, v145
	v_mov_b32_e32 v177, v146
	v_mov_b32_e32 v145, v147
	v_pk_add_f32 v[144:145], v[176:177], v[144:145]
	s_nop 0
	v_add_f32_e32 v144, v144, v145
	v_fmamk_f32 v144, v144, 0x3c000000, v217
	v_cmp_gt_f32_e32 vcc, s92, v144
	v_mul_f32_e32 v145, 0x4f800000, v144
	s_nop 0
	v_cndmask_b32_e32 v144, v144, v145, vcc
	v_sqrt_f32_e32 v145, v144
	s_nop 0
	v_add_u32_e32 v146, -1, v145
	v_fma_f32 v147, -v146, v145, v144
	v_cmp_ge_f32_e64 s[6:7], 0, v147
	v_add_u32_e32 v147, 1, v145
	s_nop 0
	v_cndmask_b32_e64 v146, v145, v146, s[6:7]
	v_fma_f32 v145, -v147, v145, v144
	v_cmp_lt_f32_e64 s[6:7], 0, v145
	s_nop 1
	v_cndmask_b32_e64 v145, v146, v147, s[6:7]
	v_mul_f32_e32 v146, 0x37800000, v145
	v_cndmask_b32_e32 v145, v145, v146, vcc
	v_cmp_class_f32_e32 vcc, v144, v218
	s_nop 1
	v_cndmask_b32_e32 v144, v145, v144, vcc
	v_div_scale_f32 v145, s[0:1], v144, v144, 1.0
	v_rcp_f32_e32 v146, v145
	s_nop 0
	v_fma_f32 v147, -v145, v146, 1.0
	v_fmac_f32_e32 v146, v147, v146
	v_div_scale_f32 v147, vcc, 1.0, v144, 1.0
	v_mul_f32_e32 v163, v147, v146
	v_fma_f32 v165, -v145, v163, v147
	v_fmac_f32_e32 v163, v165, v146
	v_fma_f32 v145, -v145, v163, v147
	v_div_fmas_f32 v145, v145, v146, v163
	v_div_fixup_f32 v144, v145, v144, 1.0
	v_pk_mul_f32 v[40:41], v[40:41], v[144:145] op_sel_hi:[1,0]
	v_pk_mul_f32 v[42:43], v[42:43], v[144:145] op_sel_hi:[1,0]
	v_pk_mul_f32 v[46:47], v[46:47], v[144:145] op_sel_hi:[1,0]
	v_pk_mul_f32 v[44:45], v[44:45], v[144:145] op_sel_hi:[1,0]
	v_pk_mul_f32 v[42:43], v[106:107], v[42:43]
	v_pk_mul_f32 v[144:145], v[104:105], v[40:41]
	v_pk_mul_f32 v[146:147], v[108:109], v[44:45]
	v_pk_mul_f32 v[46:47], v[110:111], v[46:47]
	s_nop 0
	v_pk_mul_f32 v[44:45], v[140:141], v[144:145]
	v_pk_mul_f32 v[40:41], v[142:143], v[42:43]
	v_pk_fma_f32 v[44:45], v[136:137], v[146:147], v[44:45] neg_lo:[0,0,1] neg_hi:[0,0,1]
	v_pk_fma_f32 v[40:41], v[138:139], v[46:47], v[40:41] neg_lo:[0,0,1] neg_hi:[0,0,1]
	v_pk_mul_f32 v[146:147], v[140:141], v[146:147]
	v_pk_mul_f32 v[46:47], v[142:143], v[46:47]
	s_nop 0
	v_pk_fma_f32 v[42:43], v[138:139], v[42:43], v[46:47]
	v_pk_fma_f32 v[46:47], v[136:137], v[144:145], v[146:147]
	v_cvt_pk_bf16_f32 v144, v44, v45
	v_cvt_pk_bf16_f32 v145, v40, v41
	v_cvt_pk_bf16_f32 v146, v46, v47
	v_cvt_pk_bf16_f32 v147, v42, v43
	global_store_dwordx2 v[174:175], v[144:145], off
	global_store_dwordx2 v[174:175], v[146:147], off offset:128
	s_waitcnt lgkmcnt(0)
	v_mov_b32_e32 v144, v171
	v_mov_b32_e32 v145, v172
	v_mov_b32_e32 v171, v173
	v_pk_add_f32 v[144:145], v[144:145], v[170:171]
	s_nop 0
	v_add_f32_e32 v144, v144, v145
	v_fmamk_f32 v144, v144, 0x3c000000, v217
	v_cmp_gt_f32_e32 vcc, s92, v144
	v_mul_f32_e32 v145, 0x4f800000, v144
	s_nop 0
	v_cndmask_b32_e32 v144, v144, v145, vcc
	v_sqrt_f32_e32 v145, v144
	s_nop 0
	v_add_u32_e32 v146, -1, v145
	v_fma_f32 v147, -v146, v145, v144
	v_cmp_ge_f32_e64 s[6:7], 0, v147
	v_add_u32_e32 v147, 1, v145
	s_nop 0
	v_cndmask_b32_e64 v146, v145, v146, s[6:7]
	v_fma_f32 v145, -v147, v145, v144
	v_cmp_lt_f32_e64 s[6:7], 0, v145
	s_nop 1
	v_cndmask_b32_e64 v145, v146, v147, s[6:7]
	v_mul_f32_e32 v146, 0x37800000, v145
	v_cndmask_b32_e32 v145, v145, v146, vcc
	v_cmp_class_f32_e32 vcc, v144, v218
	s_nop 1
	v_cndmask_b32_e32 v144, v145, v144, vcc
	v_div_scale_f32 v145, s[0:1], v144, v144, 1.0
	v_rcp_f32_e32 v146, v145
	s_nop 0
	v_fma_f32 v147, -v145, v146, 1.0
	v_fmac_f32_e32 v146, v147, v146
	v_div_scale_f32 v147, vcc, 1.0, v144, 1.0
	v_mul_f32_e32 v163, v147, v146
	v_fma_f32 v165, -v145, v163, v147
	v_fmac_f32_e32 v163, v165, v146
	v_fma_f32 v145, -v145, v163, v147
	v_div_fmas_f32 v145, v145, v146, v163
	v_div_fixup_f32 v144, v145, v144, 1.0
	v_pk_mul_f32 v[34:35], v[34:35], v[144:145] op_sel_hi:[1,0]
	v_pk_mul_f32 v[38:39], v[38:39], v[144:145] op_sel_hi:[1,0]
	v_pk_mul_f32 v[36:37], v[36:37], v[144:145] op_sel_hi:[1,0]
	v_pk_mul_f32 v[32:33], v[32:33], v[144:145] op_sel_hi:[1,0]
	v_pk_mul_f32 v[34:35], v[106:107], v[34:35]
	v_pk_mul_f32 v[146:147], v[108:109], v[36:37]
	v_pk_mul_f32 v[38:39], v[110:111], v[38:39]
	v_pk_mul_f32 v[144:145], v[104:105], v[32:33]
	v_pk_mul_f32 v[32:33], v[142:143], v[34:35]
	v_pk_mul_f32 v[36:37], v[140:141], v[144:145]
	v_pk_fma_f32 v[32:33], v[138:139], v[38:39], v[32:33] neg_lo:[0,0,1] neg_hi:[0,0,1]
	v_pk_mul_f32 v[140:141], v[140:141], v[146:147]
	v_pk_mul_f32 v[38:39], v[142:143], v[38:39]
	v_pk_fma_f32 v[36:37], v[136:137], v[146:147], v[36:37] neg_lo:[0,0,1] neg_hi:[0,0,1]
	v_pk_fma_f32 v[34:35], v[138:139], v[34:35], v[38:39]
	v_pk_fma_f32 v[38:39], v[136:137], v[144:145], v[140:141]
	v_add_co_u32_e32 v140, vcc, s93, v174
	v_add_u32_e32 v144, 0xa0, v162
	v_cvt_pk_bf16_f32 v136, v36, v37
	v_cvt_pk_bf16_f32 v137, v32, v33
	v_addc_co_u32_e32 v141, vcc, 0, v175, vcc
	v_ashrrev_i32_e32 v145, 31, v144
	v_cvt_pk_bf16_f32 v138, v38, v39
	v_cvt_pk_bf16_f32 v139, v34, v35
	global_store_dwordx2 v[140:141], v[136:137], off
	global_store_dwordx2 v[140:141], v[138:139], off offset:128
	v_lshlrev_b64 v[136:137], 6, v[144:145]
	v_lshl_add_u64 v[136:137], v[136:137], 0, s[64:65]
	v_lshlrev_b64 v[140:141], 2, v[136:137]
	v_lshl_add_u64 v[136:137], s[28:29], 0, v[140:141]
	v_lshl_add_u64 v[140:141], s[40:41], 0, v[140:141]
	v_lshl_add_u64 v[136:137], v[136:137], 0, v[168:169]
	v_lshl_add_u64 v[140:141], v[140:141], 0, v[168:169]
	v_mov_b64_e32 v[136:137], v[238:239]
	v_mov_b64_e32 v[138:139], v[240:241]
	v_lshl_add_u32 v163, v144, 5, s51
	v_mov_b64_e32 v[140:141], v[242:243]
	v_mov_b64_e32 v[142:143], v[244:245]
	v_lshlrev_b64 v[144:145], 8, v[144:145]
	v_lshl_add_u64 v[174:175], v[166:167], 0, v[144:145]
	ds_read_b128 v[144:147], v163
	ds_read_b128 v[170:173], v163 offset:16
	s_waitcnt lgkmcnt(1)
	v_mov_b32_e32 v176, v145
	v_mov_b32_e32 v177, v146
	v_mov_b32_e32 v145, v147
	v_pk_add_f32 v[144:145], v[176:177], v[144:145]
	s_nop 0
	v_add_f32_e32 v144, v144, v145
	v_fmamk_f32 v144, v144, 0x3c000000, v217
	v_cmp_gt_f32_e32 vcc, s92, v144
	v_mul_f32_e32 v145, 0x4f800000, v144
	s_nop 0
	v_cndmask_b32_e32 v144, v144, v145, vcc
	v_sqrt_f32_e32 v145, v144
	s_nop 0
	v_add_u32_e32 v146, -1, v145
	v_fma_f32 v147, -v146, v145, v144
	v_cmp_ge_f32_e64 s[6:7], 0, v147
	v_add_u32_e32 v147, 1, v145
	s_nop 0
	v_cndmask_b32_e64 v146, v145, v146, s[6:7]
	v_fma_f32 v145, -v147, v145, v144
	v_cmp_lt_f32_e64 s[6:7], 0, v145
	s_nop 1
	v_cndmask_b32_e64 v145, v146, v147, s[6:7]
	v_mul_f32_e32 v146, 0x37800000, v145
	v_cndmask_b32_e32 v145, v145, v146, vcc
	v_cmp_class_f32_e32 vcc, v144, v218
	s_nop 1
	v_cndmask_b32_e32 v144, v145, v144, vcc
	v_div_scale_f32 v145, s[0:1], v144, v144, 1.0
	v_rcp_f32_e32 v146, v145
	s_nop 0
	v_fma_f32 v147, -v145, v146, 1.0
	v_fmac_f32_e32 v146, v147, v146
	v_div_scale_f32 v147, vcc, 1.0, v144, 1.0
	v_mul_f32_e32 v163, v147, v146
	v_fma_f32 v165, -v145, v163, v147
	v_fmac_f32_e32 v163, v165, v146
	v_fma_f32 v145, -v145, v163, v147
	v_div_fmas_f32 v145, v145, v146, v163
	v_div_fixup_f32 v144, v145, v144, 1.0
	v_pk_mul_f32 v[24:25], v[24:25], v[144:145] op_sel_hi:[1,0]
	v_pk_mul_f32 v[26:27], v[26:27], v[144:145] op_sel_hi:[1,0]
	v_pk_mul_f32 v[30:31], v[30:31], v[144:145] op_sel_hi:[1,0]
	v_pk_mul_f32 v[28:29], v[28:29], v[144:145] op_sel_hi:[1,0]
	v_pk_mul_f32 v[26:27], v[106:107], v[26:27]
	v_pk_mul_f32 v[144:145], v[104:105], v[24:25]
	v_pk_mul_f32 v[146:147], v[108:109], v[28:29]
	v_pk_mul_f32 v[30:31], v[110:111], v[30:31]
	s_nop 0
	v_pk_mul_f32 v[28:29], v[140:141], v[144:145]
	v_pk_mul_f32 v[24:25], v[142:143], v[26:27]
	v_pk_fma_f32 v[28:29], v[136:137], v[146:147], v[28:29] neg_lo:[0,0,1] neg_hi:[0,0,1]
	v_pk_fma_f32 v[24:25], v[138:139], v[30:31], v[24:25] neg_lo:[0,0,1] neg_hi:[0,0,1]
	v_pk_mul_f32 v[146:147], v[140:141], v[146:147]
	v_pk_mul_f32 v[30:31], v[142:143], v[30:31]
	s_nop 0
	v_pk_fma_f32 v[26:27], v[138:139], v[26:27], v[30:31]
	v_pk_fma_f32 v[30:31], v[136:137], v[144:145], v[146:147]
	v_cvt_pk_bf16_f32 v144, v28, v29
	v_cvt_pk_bf16_f32 v145, v24, v25
	v_cvt_pk_bf16_f32 v146, v30, v31
	v_cvt_pk_bf16_f32 v147, v26, v27
	global_store_dwordx2 v[174:175], v[144:145], off
	global_store_dwordx2 v[174:175], v[146:147], off offset:128
	s_waitcnt lgkmcnt(0)
	v_mov_b32_e32 v144, v171
	v_mov_b32_e32 v145, v172
	v_mov_b32_e32 v171, v173
	v_pk_add_f32 v[144:145], v[144:145], v[170:171]
	s_nop 0
	v_add_f32_e32 v144, v144, v145
	v_fmamk_f32 v144, v144, 0x3c000000, v217
	v_cmp_gt_f32_e32 vcc, s92, v144
	v_mul_f32_e32 v145, 0x4f800000, v144
	s_nop 0
	v_cndmask_b32_e32 v144, v144, v145, vcc
	v_sqrt_f32_e32 v145, v144
	s_nop 0
	v_add_u32_e32 v146, -1, v145
	v_fma_f32 v147, -v146, v145, v144
	v_cmp_ge_f32_e64 s[6:7], 0, v147
	v_add_u32_e32 v147, 1, v145
	s_nop 0
	v_cndmask_b32_e64 v146, v145, v146, s[6:7]
	v_fma_f32 v145, -v147, v145, v144
	v_cmp_lt_f32_e64 s[6:7], 0, v145
	s_nop 1
	v_cndmask_b32_e64 v145, v146, v147, s[6:7]
	v_mul_f32_e32 v146, 0x37800000, v145
	v_cndmask_b32_e32 v145, v145, v146, vcc
	v_cmp_class_f32_e32 vcc, v144, v218
	s_nop 1
	v_cndmask_b32_e32 v144, v145, v144, vcc
	v_div_scale_f32 v145, s[0:1], v144, v144, 1.0
	v_rcp_f32_e32 v146, v145
	s_nop 0
	v_fma_f32 v147, -v145, v146, 1.0
	v_fmac_f32_e32 v146, v147, v146
	v_div_scale_f32 v147, vcc, 1.0, v144, 1.0
	v_mul_f32_e32 v163, v147, v146
	v_fma_f32 v165, -v145, v163, v147
	v_fmac_f32_e32 v163, v165, v146
	v_fma_f32 v145, -v145, v163, v147
	v_div_fmas_f32 v145, v145, v146, v163
	v_div_fixup_f32 v144, v145, v144, 1.0
	v_pk_mul_f32 v[18:19], v[18:19], v[144:145] op_sel_hi:[1,0]
	v_pk_mul_f32 v[22:23], v[22:23], v[144:145] op_sel_hi:[1,0]
	v_pk_mul_f32 v[20:21], v[20:21], v[144:145] op_sel_hi:[1,0]
	v_pk_mul_f32 v[16:17], v[16:17], v[144:145] op_sel_hi:[1,0]
	v_pk_mul_f32 v[18:19], v[106:107], v[18:19]
	v_pk_mul_f32 v[146:147], v[108:109], v[20:21]
	v_pk_mul_f32 v[22:23], v[110:111], v[22:23]
	v_pk_mul_f32 v[144:145], v[104:105], v[16:17]
	v_pk_mul_f32 v[16:17], v[142:143], v[18:19]
	v_pk_mul_f32 v[20:21], v[140:141], v[144:145]
	v_pk_fma_f32 v[16:17], v[138:139], v[22:23], v[16:17] neg_lo:[0,0,1] neg_hi:[0,0,1]
	v_pk_mul_f32 v[140:141], v[140:141], v[146:147]
	v_pk_mul_f32 v[22:23], v[142:143], v[22:23]
	v_pk_fma_f32 v[20:21], v[136:137], v[146:147], v[20:21] neg_lo:[0,0,1] neg_hi:[0,0,1]
	v_pk_fma_f32 v[18:19], v[138:139], v[18:19], v[22:23]
	v_pk_fma_f32 v[22:23], v[136:137], v[144:145], v[140:141]
	v_add_co_u32_e32 v140, vcc, s93, v174
	v_add_u32_e32 v144, 0xb0, v162
	v_cvt_pk_bf16_f32 v136, v20, v21
	v_cvt_pk_bf16_f32 v137, v16, v17
	v_addc_co_u32_e32 v141, vcc, 0, v175, vcc
	v_ashrrev_i32_e32 v145, 31, v144
	v_cvt_pk_bf16_f32 v138, v22, v23
	v_cvt_pk_bf16_f32 v139, v18, v19
	global_store_dwordx2 v[140:141], v[136:137], off
	global_store_dwordx2 v[140:141], v[138:139], off offset:128
	v_lshlrev_b64 v[136:137], 6, v[144:145]
	v_lshl_add_u64 v[136:137], v[136:137], 0, s[64:65]
	v_lshlrev_b64 v[140:141], 2, v[136:137]
	v_lshl_add_u64 v[136:137], s[28:29], 0, v[140:141]
	v_lshl_add_u64 v[140:141], s[40:41], 0, v[140:141]
	v_lshl_add_u64 v[136:137], v[136:137], 0, v[168:169]
	v_lshl_add_u64 v[140:141], v[140:141], 0, v[168:169]
	v_mov_b64_e32 v[136:137], v[178:179]
	v_mov_b64_e32 v[138:139], v[180:181]
	v_lshl_add_u32 v165, v144, 5, s51
	v_mov_b64_e32 v[140:141], v[182:183]
	v_mov_b64_e32 v[142:143], v[184:185]
	v_lshlrev_b64 v[144:145], 8, v[144:145]
	v_lshl_add_u64 v[162:163], v[166:167], 0, v[144:145]
	ds_read_b128 v[144:147], v165
	ds_read_b128 v[166:169], v165 offset:16
	s_waitcnt lgkmcnt(1)
	v_mov_b32_e32 v170, v145
	v_mov_b32_e32 v171, v146
	v_mov_b32_e32 v145, v147
	v_pk_add_f32 v[144:145], v[170:171], v[144:145]
	s_nop 0
	v_add_f32_e32 v144, v144, v145
	v_fmamk_f32 v144, v144, 0x3c000000, v217
	v_cmp_gt_f32_e32 vcc, s92, v144
	v_mul_f32_e32 v145, 0x4f800000, v144
	s_nop 0
	v_cndmask_b32_e32 v144, v144, v145, vcc
	v_sqrt_f32_e32 v145, v144
	s_nop 0
	v_add_u32_e32 v146, -1, v145
	v_fma_f32 v147, -v146, v145, v144
	v_cmp_ge_f32_e64 s[6:7], 0, v147
	v_add_u32_e32 v147, 1, v145
	s_nop 0
	v_cndmask_b32_e64 v146, v145, v146, s[6:7]
	v_fma_f32 v145, -v147, v145, v144
	v_cmp_lt_f32_e64 s[6:7], 0, v145
	s_nop 1
	v_cndmask_b32_e64 v145, v146, v147, s[6:7]
	v_mul_f32_e32 v146, 0x37800000, v145
	v_cndmask_b32_e32 v145, v145, v146, vcc
	v_cmp_class_f32_e32 vcc, v144, v218
	s_nop 1
	v_cndmask_b32_e32 v144, v145, v144, vcc
	v_div_scale_f32 v145, s[0:1], v144, v144, 1.0
	v_rcp_f32_e32 v146, v145
	s_nop 0
	v_fma_f32 v147, -v145, v146, 1.0
	v_fmac_f32_e32 v146, v147, v146
	v_div_scale_f32 v147, vcc, 1.0, v144, 1.0
	v_mul_f32_e32 v165, v147, v146
	v_fma_f32 v170, -v145, v165, v147
	v_fmac_f32_e32 v165, v170, v146
	v_fma_f32 v145, -v145, v165, v147
	v_div_fmas_f32 v145, v145, v146, v165
	v_div_fixup_f32 v144, v145, v144, 1.0
	v_pk_mul_f32 v[8:9], v[8:9], v[144:145] op_sel_hi:[1,0]
	v_pk_mul_f32 v[10:11], v[10:11], v[144:145] op_sel_hi:[1,0]
	v_pk_mul_f32 v[14:15], v[14:15], v[144:145] op_sel_hi:[1,0]
	v_pk_mul_f32 v[12:13], v[12:13], v[144:145] op_sel_hi:[1,0]
	v_pk_mul_f32 v[10:11], v[106:107], v[10:11]
	v_pk_mul_f32 v[144:145], v[104:105], v[8:9]
	v_pk_mul_f32 v[12:13], v[108:109], v[12:13]
	v_pk_mul_f32 v[146:147], v[110:111], v[14:15]
	s_waitcnt vmcnt(0)
	v_pk_mul_f32 v[14:15], v[140:141], v[144:145]
	v_pk_mul_f32 v[8:9], v[142:143], v[10:11]
	v_pk_fma_f32 v[14:15], v[136:137], v[12:13], v[14:15] neg_lo:[0,0,1] neg_hi:[0,0,1]
	v_pk_fma_f32 v[8:9], v[138:139], v[146:147], v[8:9] neg_lo:[0,0,1] neg_hi:[0,0,1]
	v_pk_mul_f32 v[12:13], v[140:141], v[12:13]
	v_pk_mul_f32 v[146:147], v[142:143], v[146:147]
	v_pk_fma_f32 v[12:13], v[136:137], v[144:145], v[12:13]
	v_pk_fma_f32 v[10:11], v[138:139], v[10:11], v[146:147]
	v_cvt_pk_bf16_f32 v144, v14, v15
	v_cvt_pk_bf16_f32 v145, v8, v9
	v_cvt_pk_bf16_f32 v146, v12, v13
	v_cvt_pk_bf16_f32 v147, v10, v11
	global_store_dwordx2 v[162:163], v[144:145], off
	global_store_dwordx2 v[162:163], v[146:147], off offset:128
	s_waitcnt lgkmcnt(0)
	v_mov_b32_e32 v144, v167
	v_mov_b32_e32 v145, v168
	v_mov_b32_e32 v167, v169
	v_pk_add_f32 v[144:145], v[144:145], v[166:167]
	s_nop 0
	v_add_f32_e32 v144, v144, v145
	v_fmamk_f32 v144, v144, 0x3c000000, v217
	v_cmp_gt_f32_e32 vcc, s92, v144
	v_mul_f32_e32 v145, 0x4f800000, v144
	s_nop 0
	v_cndmask_b32_e32 v144, v144, v145, vcc
	v_sqrt_f32_e32 v145, v144
	s_nop 0
	v_add_u32_e32 v146, -1, v145
	v_fma_f32 v147, -v146, v145, v144
	v_cmp_ge_f32_e64 s[6:7], 0, v147
	v_add_u32_e32 v147, 1, v145
	s_nop 0
	v_cndmask_b32_e64 v146, v145, v146, s[6:7]
	v_fma_f32 v145, -v147, v145, v144
	v_cmp_lt_f32_e64 s[6:7], 0, v145
	s_nop 1
	v_cndmask_b32_e64 v145, v146, v147, s[6:7]
	v_mul_f32_e32 v146, 0x37800000, v145
	v_cndmask_b32_e32 v145, v145, v146, vcc
	v_cmp_class_f32_e32 vcc, v144, v218
	s_nop 1
	v_cndmask_b32_e32 v144, v145, v144, vcc
	v_div_scale_f32 v145, s[0:1], v144, v144, 1.0
	v_rcp_f32_e32 v146, v145
	s_nop 0
	v_fma_f32 v147, -v145, v146, 1.0
	v_fmac_f32_e32 v146, v147, v146
	v_div_scale_f32 v147, vcc, 1.0, v144, 1.0
	v_mul_f32_e32 v165, v147, v146
	v_fma_f32 v166, -v145, v165, v147
	v_fmac_f32_e32 v165, v166, v146
	v_fma_f32 v145, -v145, v165, v147
	v_div_fmas_f32 v145, v145, v146, v165
	v_div_fixup_f32 v144, v145, v144, 1.0
	v_pk_mul_f32 v[0:1], v[0:1], v[144:145] op_sel_hi:[1,0]
	v_pk_mul_f32 v[2:3], v[2:3], v[144:145] op_sel_hi:[1,0]
	v_pk_mul_f32 v[6:7], v[6:7], v[144:145] op_sel_hi:[1,0]
	v_pk_mul_f32 v[4:5], v[4:5], v[144:145] op_sel_hi:[1,0]
	v_pk_mul_f32 v[2:3], v[106:107], v[2:3]
	v_pk_mul_f32 v[104:105], v[104:105], v[0:1]
	v_pk_mul_f32 v[108:109], v[108:109], v[4:5]
	v_pk_mul_f32 v[6:7], v[110:111], v[6:7]
	v_pk_mul_f32 v[4:5], v[140:141], v[104:105]
	v_pk_mul_f32 v[0:1], v[142:143], v[2:3]
	v_pk_fma_f32 v[4:5], v[136:137], v[108:109], v[4:5] neg_lo:[0,0,1] neg_hi:[0,0,1]
	v_pk_fma_f32 v[0:1], v[138:139], v[6:7], v[0:1] neg_lo:[0,0,1] neg_hi:[0,0,1]
	v_pk_mul_f32 v[106:107], v[140:141], v[108:109]
	v_pk_mul_f32 v[6:7], v[142:143], v[6:7]
	v_add_co_u32_e32 v108, vcc, 0x80000, v162
	v_pk_fma_f32 v[2:3], v[138:139], v[2:3], v[6:7]
	v_pk_fma_f32 v[6:7], v[136:137], v[104:105], v[106:107]
	v_cvt_pk_bf16_f32 v104, v4, v5
	v_cvt_pk_bf16_f32 v105, v0, v1
	v_addc_co_u32_e32 v109, vcc, 0, v163, vcc
	v_cvt_pk_bf16_f32 v106, v6, v7
	v_cvt_pk_bf16_f32 v107, v2, v3
	global_store_dwordx2 v[108:109], v[104:105], off
	global_store_dwordx2 v[108:109], v[106:107], off offset:128
	s_cbranch_scc1 .LBB0_261
	v_pk_add_f32 v[104:105], v[132:133], 0 op_sel_hi:[1,0]
	v_pk_add_f32 v[106:107], v[134:135], 0 op_sel_hi:[1,0]
	v_pk_add_f32 v[104:105], v[104:105], v[116:117]
	v_pk_add_f32 v[106:107], v[106:107], v[118:119]
	v_pk_add_f32 v[92:93], v[104:105], v[92:93]
	v_pk_add_f32 v[94:95], v[106:107], v[94:95]
	v_pk_add_f32 v[76:77], v[92:93], v[76:77]
	v_pk_add_f32 v[78:79], v[94:95], v[78:79]
	v_pk_add_f32 v[60:61], v[76:77], v[60:61]
	v_pk_add_f32 v[62:63], v[78:79], v[62:63]
	v_pk_add_f32 v[44:45], v[60:61], v[44:45]
	v_pk_add_f32 v[46:47], v[62:63], v[46:47]
	v_pk_add_f32 v[28:29], v[44:45], v[28:29]
	v_pk_add_f32 v[30:31], v[46:47], v[30:31]
	v_pk_add_f32 v[14:15], v[28:29], v[14:15]
	v_pk_add_f32 v[12:13], v[30:31], v[12:13]
	ds_swizzle_b32 v28, v14 offset:swizzle(SWAP,1)
	ds_swizzle_b32 v29, v12 offset:swizzle(SWAP,1)
	v_cmp_eq_u32_e32 vcc, 0, v152
	s_waitcnt lgkmcnt(1)
	v_add_f32_e32 v14, v14, v28
	s_waitcnt lgkmcnt(0)
	v_add_f32_e32 v12, v12, v29
	ds_swizzle_b32 v28, v14 offset:swizzle(SWAP,2)
	ds_swizzle_b32 v29, v12 offset:swizzle(SWAP,2)
	s_waitcnt lgkmcnt(1)
	v_add_f32_e32 v14, v14, v28
	s_waitcnt lgkmcnt(0)
	v_add_f32_e32 v12, v12, v29
	ds_swizzle_b32 v28, v14 offset:swizzle(SWAP,4)
	ds_swizzle_b32 v29, v12 offset:swizzle(SWAP,4)
	s_waitcnt lgkmcnt(1)
	v_add_f32_e32 v14, v14, v28
	s_waitcnt lgkmcnt(0)
	v_add_f32_e32 v29, v12, v29
	ds_swizzle_b32 v28, v14 offset:swizzle(SWAP,8)
	ds_swizzle_b32 v30, v29 offset:swizzle(SWAP,8)
	v_lshl_add_u32 v12, v164, 2, s86
	s_and_saveexec_b64 s[6:7], vcc
	s_cbranch_execz .LBB0_244
	s_waitcnt lgkmcnt(0)
	v_add_f32_e32 v29, v29, v30
	v_add_f32_e32 v14, v14, v28
	ds_write2st64_b32 v12, v14, v29 offset1:1
